# bf16 residual fast paths (G4, G2 layer 1): each group's store issued right after its pack with exact mixed load/store vmcnt counts, so the store drain starts during the epilogue
# speedup vs baseline: 1.0010x; 1.0010x over previous
; __device__ __forceinline__ unsigned cvt_pk_bf16(float lo, float hi) { unsigned r; asm volatile("v_cvt_pk_bf16_f32 %0, %1, %2" : "=v"(r) : "v"(lo), "v"(hi)); return r; }
;     __device__ __forceinline__ void operator()(const f32x4 (&acc)[2][2][4][2], const Unit& u, int wr, int wc, int fr, int fq) const {
;         const bool lat = u.pm < NLAT / BM; const int bb = lat ? (u.pm >> 5) : 4;
;         const int row0 = (lat ? u.pm * BM : u.pm * BM - NLAT) + wr * 64 + fr, col0 = u.pn * BM + wc * 32 + 8 * fq;
;         f32x4 g[2][2];
; #pragma unroll
;         for (int bj = 0; bj < 2; ++bj)
; #pragma unroll
;             for (int n = 0; n < 2; ++n) g[bj][n] = *(const f32x4*)(gate + bb * 6144 + col0 + bj * HALF + n * 4);
; #pragma unroll
;         for (int ai = 0; ai < 2; ++ai)
; #pragma unroll
;             for (int m = 0; m < 4; ++m) {
;                 const size_t off = (size_t)(row0 + ai * HALF + m * 16) * 1024 + col0;
; #pragma unroll
;                 for (int bj = 0; bj < 2; ++bj) {
;                     f32x4 b0, b1;
;                     if (!lat) { b0 = *(const f32x4*)(baseC + off + bj * HALF); b1 = *(const f32x4*)(baseC + off + bj * HALF + 4); }
;                     else if (baseLf) { b0 = *(const f32x4*)(baseLf + off + bj * HALF); b1 = *(const f32x4*)(baseLf + off + bj * HALF + 4); }
;                     else { const u32x4 w = *(const u32x4*)(baseLb + off + bj * HALF);
;                         b0 = (f32x4){__builtin_bit_cast(float, w.x << 16), __builtin_bit_cast(float, w.x & 0xffff0000u), __builtin_bit_cast(float, w.y << 16), __builtin_bit_cast(float, w.y & 0xffff0000u)};
;                         b1 = (f32x4){__builtin_bit_cast(float, w.z << 16), __builtin_bit_cast(float, w.z & 0xffff0000u), __builtin_bit_cast(float, w.w << 16), __builtin_bit_cast(float, w.w & 0xffff0000u)}; }
;                     const f32x4 o0 = b0 + g[bj][0] * acc[ai][bj][m][0], o1 = b1 + g[bj][1] * acc[ai][bj][m][1];
;                     if (!lat) { *(f32x4*)(outC + off + bj * HALF) = o0; *(f32x4*)(outC + off + bj * HALF + 4) = o1; }
;                     else { u32x4 w; w.x = cvt_pk_bf16(o0.x, o0.y); w.y = cvt_pk_bf16(o0.z, o0.w); w.z = cvt_pk_bf16(o1.x, o1.y); w.w = cvt_pk_bf16(o1.z, o1.w); *(u32x4*)(outL + off + bj * HALF) = w; }
.LBB0_565:
	s_cmpk_gt_i32 s42, 0x7f
	s_cselect_b64 s[48:49], -1, 0
	s_lshl_b32 s15, s42, 8
	s_lshr_b32 s14, s42, 5
	s_add_i32 s16, s15, 0xffff8000
	s_cmpk_lt_i32 s42, 0x80
	s_cselect_b64 s[12:13], -1, 0
	s_mulk_i32 s14, 0x1800
	s_and_b64 vcc, s[12:13], exec
	s_cselect_b32 s12, s14, 0x6000
	s_cselect_b32 s14, s15, s16
	s_ashr_i32 s13, s12, 31
	s_lshl_b64 s[12:13], s[12:13], 2
	v_lshl_or_b32 v162, s40, 8, v172
	s_add_u32 s12, s69, s12
	s_addc_u32 s13, s93, s13
	v_ashrrev_i32_e32 v163, 31, v162
	v_lshl_add_u64 v[44:45], v[162:163], 2, s[12:13]
	global_load_dwordx4 v[56:59], v[44:45], off offset:16
	global_load_dwordx4 v[60:63], v[44:45], off
	global_load_dwordx4 v[40:43], v[44:45], off offset:528
	s_nop 0
	global_load_dwordx4 v[44:47], v[44:45], off offset:512
	v_add_u32_e32 v164, s14, v170
	v_ashrrev_i32_e32 v165, 31, v164
	v_lshlrev_b64 v[144:145], 10, v[164:165]
	v_lshl_add_u64 v[166:167], v[144:145], 0, v[162:163]
	s_mov_b64 s[40:41], -1
	v_lshl_add_u64 v[168:169], v[166:167], 2, s[46:47]
	s_cmp_eq_u64 s[48:49], 0
	s_cbranch_scc0 .Lep2_ctx
	s_cmp_eq_u64 s[52:53], 0
	s_cbranch_scc0 .Lep2_f32
	v_lshl_add_u64 v[168:169], v[166:167], 1, s[6:7]
	s_mov_b64 s[12:13], 0x8000
	s_mov_b64 s[14:15], 0x28000
	v_mov_b32_e32 v164, v168
	v_mov_b32_e32 v165, v169
	global_load_dwordx4 v[174:177], v[168:169], off
	global_load_dwordx4 v[178:181], v[168:169], off offset:256
	v_lshl_add_u64 v[168:169], v[168:169], 0, s[12:13]
	global_load_dwordx4 v[182:185], v[168:169], off
	global_load_dwordx4 v[186:189], v[168:169], off offset:256
	v_lshl_add_u64 v[168:169], v[168:169], 0, s[12:13]
	global_load_dwordx4 v[190:193], v[168:169], off
	global_load_dwordx4 v[194:197], v[168:169], off offset:256
	v_lshl_add_u64 v[168:169], v[168:169], 0, s[12:13]
	global_load_dwordx4 v[198:201], v[168:169], off
	global_load_dwordx4 v[202:205], v[168:169], off offset:256
	s_waitcnt vmcnt(7)
	v_lshlrev_b32_e32 v144, 16, v174
	v_and_b32_e32 v145, 0xffff0000, v174
	v_lshlrev_b32_e32 v146, 16, v175
	v_and_b32_e32 v147, 0xffff0000, v175
	v_lshlrev_b32_e32 v148, 16, v176
	v_and_b32_e32 v149, 0xffff0000, v176
	v_lshlrev_b32_e32 v150, 16, v177
	v_and_b32_e32 v151, 0xffff0000, v177
	v_lshl_add_u64 v[168:169], v[168:169], 0, s[14:15]
	global_load_dwordx4 v[174:177], v[168:169], off
	v_pk_fma_f32 v[140:141], v[140:141], v[60:61], v[144:145]
	v_pk_fma_f32 v[142:143], v[142:143], v[62:63], v[146:147]
	v_pk_fma_f32 v[136:137], v[136:137], v[56:57], v[148:149]
	v_pk_fma_f32 v[138:139], v[138:139], v[58:59], v[150:151]
	v_cvt_pk_bf16_f32 v140, v140, v141
	v_cvt_pk_bf16_f32 v141, v142, v143
	v_cvt_pk_bf16_f32 v142, v136, v137
	v_cvt_pk_bf16_f32 v143, v138, v139
	global_store_dwordx4 v[164:165], v[140:143], off
	s_waitcnt vmcnt(8)
	v_lshlrev_b32_e32 v144, 16, v178
	v_and_b32_e32 v145, 0xffff0000, v178
	v_lshlrev_b32_e32 v146, 16, v179
	v_and_b32_e32 v147, 0xffff0000, v179
	v_lshlrev_b32_e32 v148, 16, v180
	v_and_b32_e32 v149, 0xffff0000, v180
	v_lshlrev_b32_e32 v150, 16, v181
	v_and_b32_e32 v151, 0xffff0000, v181
	global_load_dwordx4 v[178:181], v[168:169], off offset:256
	v_pk_fma_f32 v[132:133], v[132:133], v[44:45], v[144:145]
	v_pk_fma_f32 v[134:135], v[134:135], v[46:47], v[146:147]
	v_pk_fma_f32 v[128:129], v[128:129], v[40:41], v[148:149]
	v_pk_fma_f32 v[130:131], v[130:131], v[42:43], v[150:151]
	v_cvt_pk_bf16_f32 v132, v132, v133
	v_cvt_pk_bf16_f32 v133, v134, v135
	v_cvt_pk_bf16_f32 v134, v128, v129
	v_cvt_pk_bf16_f32 v135, v130, v131
	global_store_dwordx4 v[164:165], v[132:135], off offset:256
	s_waitcnt vmcnt(9)
	v_lshlrev_b32_e32 v144, 16, v182
	v_and_b32_e32 v145, 0xffff0000, v182
	v_lshlrev_b32_e32 v146, 16, v183
	v_and_b32_e32 v147, 0xffff0000, v183
	v_lshlrev_b32_e32 v148, 16, v184
	v_and_b32_e32 v149, 0xffff0000, v184
	v_lshlrev_b32_e32 v150, 16, v185
	v_and_b32_e32 v151, 0xffff0000, v185
	v_lshl_add_u64 v[168:169], v[168:169], 0, s[12:13]
	global_load_dwordx4 v[182:185], v[168:169], off
	v_pk_fma_f32 v[124:125], v[124:125], v[60:61], v[144:145]
	v_pk_fma_f32 v[126:127], v[126:127], v[62:63], v[146:147]
	v_pk_fma_f32 v[120:121], v[120:121], v[56:57], v[148:149]
	v_pk_fma_f32 v[122:123], v[122:123], v[58:59], v[150:151]
	v_cvt_pk_bf16_f32 v124, v124, v125
	v_cvt_pk_bf16_f32 v125, v126, v127
	v_cvt_pk_bf16_f32 v126, v120, v121
	v_cvt_pk_bf16_f32 v127, v122, v123
	v_lshl_add_u64 v[164:165], v[164:165], 0, s[12:13]
	global_store_dwordx4 v[164:165], v[124:127], off
	s_waitcnt vmcnt(10)
	v_lshlrev_b32_e32 v144, 16, v186
	v_and_b32_e32 v145, 0xffff0000, v186
	v_lshlrev_b32_e32 v146, 16, v187
	v_and_b32_e32 v147, 0xffff0000, v187
	v_lshlrev_b32_e32 v148, 16, v188
	v_and_b32_e32 v149, 0xffff0000, v188
	v_lshlrev_b32_e32 v150, 16, v189
	v_and_b32_e32 v151, 0xffff0000, v189
	global_load_dwordx4 v[186:189], v[168:169], off offset:256
	v_pk_fma_f32 v[116:117], v[116:117], v[44:45], v[144:145]
	v_pk_fma_f32 v[118:119], v[118:119], v[46:47], v[146:147]
	v_pk_fma_f32 v[112:113], v[112:113], v[40:41], v[148:149]
	v_pk_fma_f32 v[114:115], v[114:115], v[42:43], v[150:151]
	v_cvt_pk_bf16_f32 v116, v116, v117
	v_cvt_pk_bf16_f32 v117, v118, v119
	v_cvt_pk_bf16_f32 v118, v112, v113
	v_cvt_pk_bf16_f32 v119, v114, v115
	global_store_dwordx4 v[164:165], v[116:119], off offset:256
	s_waitcnt vmcnt(11)
; __device__ __forceinline__ unsigned cvt_pk_bf16(float lo, float hi) { unsigned r; asm volatile("v_cvt_pk_bf16_f32 %0, %1, %2" : "=v"(r) : "v"(lo), "v"(hi)); return r; }
;     __device__ __forceinline__ void operator()(const f32x4 (&acc)[2][2][4][2], const Unit& u, int wr, int wc, int fr, int fq) const {
;     ...
;                 for (int bj = 0; bj < 2; ++bj) {
;                     f32x4 b0, b1;
;                     if (!lat) { b0 = *(const f32x4*)(baseC + off + bj * HALF); b1 = *(const f32x4*)(baseC + off + bj * HALF + 4); }
;                     else if (baseLf) { b0 = *(const f32x4*)(baseLf + off + bj * HALF); b1 = *(const f32x4*)(baseLf + off + bj * HALF + 4); }
;                     else { const u32x4 w = *(const u32x4*)(baseLb + off + bj * HALF);
;                         b0 = (f32x4){__builtin_bit_cast(float, w.x << 16), __builtin_bit_cast(float, w.x & 0xffff0000u), __builtin_bit_cast(float, w.y << 16), __builtin_bit_cast(float, w.y & 0xffff0000u)};
;                         b1 = (f32x4){__builtin_bit_cast(float, w.z << 16), __builtin_bit_cast(float, w.z & 0xffff0000u), __builtin_bit_cast(float, w.w << 16), __builtin_bit_cast(float, w.w & 0xffff0000u)}; }
;                     const f32x4 o0 = b0 + g[bj][0] * acc[ai][bj][m][0], o1 = b1 + g[bj][1] * acc[ai][bj][m][1];
;                     if (!lat) { *(f32x4*)(outC + off + bj * HALF) = o0; *(f32x4*)(outC + off + bj * HALF + 4) = o1; }
;                     else { u32x4 w; w.x = cvt_pk_bf16(o0.x, o0.y); w.y = cvt_pk_bf16(o0.z, o0.w); w.z = cvt_pk_bf16(o1.x, o1.y); w.w = cvt_pk_bf16(o1.z, o1.w); *(u32x4*)(outL + off + bj * HALF) = w; }
	v_lshlrev_b32_e32 v144, 16, v190
	v_and_b32_e32 v145, 0xffff0000, v190
	v_lshlrev_b32_e32 v146, 16, v191
	v_and_b32_e32 v147, 0xffff0000, v191
	v_lshlrev_b32_e32 v148, 16, v192
	v_and_b32_e32 v149, 0xffff0000, v192
	v_lshlrev_b32_e32 v150, 16, v193
	v_and_b32_e32 v151, 0xffff0000, v193
	v_lshl_add_u64 v[168:169], v[168:169], 0, s[12:13]
	global_load_dwordx4 v[190:193], v[168:169], off
	v_pk_fma_f32 v[108:109], v[108:109], v[60:61], v[144:145]
	v_pk_fma_f32 v[110:111], v[110:111], v[62:63], v[146:147]
	v_pk_fma_f32 v[104:105], v[104:105], v[56:57], v[148:149]
	v_pk_fma_f32 v[106:107], v[106:107], v[58:59], v[150:151]
	v_cvt_pk_bf16_f32 v108, v108, v109
	v_cvt_pk_bf16_f32 v109, v110, v111
	v_cvt_pk_bf16_f32 v110, v104, v105
	v_cvt_pk_bf16_f32 v111, v106, v107
	v_lshl_add_u64 v[164:165], v[164:165], 0, s[12:13]
	global_store_dwordx4 v[164:165], v[108:111], off
	s_waitcnt vmcnt(12)
	v_lshlrev_b32_e32 v144, 16, v194
	v_and_b32_e32 v145, 0xffff0000, v194
	v_lshlrev_b32_e32 v146, 16, v195
	v_and_b32_e32 v147, 0xffff0000, v195
	v_lshlrev_b32_e32 v148, 16, v196
	v_and_b32_e32 v149, 0xffff0000, v196
	v_lshlrev_b32_e32 v150, 16, v197
	v_and_b32_e32 v151, 0xffff0000, v197
	global_load_dwordx4 v[194:197], v[168:169], off offset:256
	v_pk_fma_f32 v[100:101], v[100:101], v[44:45], v[144:145]
	v_pk_fma_f32 v[102:103], v[102:103], v[46:47], v[146:147]
	v_pk_fma_f32 v[96:97], v[96:97], v[40:41], v[148:149]
	v_pk_fma_f32 v[98:99], v[98:99], v[42:43], v[150:151]
	v_cvt_pk_bf16_f32 v100, v100, v101
	v_cvt_pk_bf16_f32 v101, v102, v103
	v_cvt_pk_bf16_f32 v102, v96, v97
	v_cvt_pk_bf16_f32 v103, v98, v99
	global_store_dwordx4 v[164:165], v[100:103], off offset:256
	s_waitcnt vmcnt(13)
	v_lshlrev_b32_e32 v144, 16, v198
	v_and_b32_e32 v145, 0xffff0000, v198
	v_lshlrev_b32_e32 v146, 16, v199
	v_and_b32_e32 v147, 0xffff0000, v199
	v_lshlrev_b32_e32 v148, 16, v200
	v_and_b32_e32 v149, 0xffff0000, v200
	v_lshlrev_b32_e32 v150, 16, v201
	v_and_b32_e32 v151, 0xffff0000, v201
	v_lshl_add_u64 v[168:169], v[168:169], 0, s[12:13]
	global_load_dwordx4 v[198:201], v[168:169], off
	v_pk_fma_f32 v[92:93], v[92:93], v[60:61], v[144:145]
	v_pk_fma_f32 v[94:95], v[94:95], v[62:63], v[146:147]
	v_pk_fma_f32 v[88:89], v[88:89], v[56:57], v[148:149]
	v_pk_fma_f32 v[90:91], v[90:91], v[58:59], v[150:151]
	v_cvt_pk_bf16_f32 v92, v92, v93
	v_cvt_pk_bf16_f32 v93, v94, v95
	v_cvt_pk_bf16_f32 v94, v88, v89
	v_cvt_pk_bf16_f32 v95, v90, v91
	v_lshl_add_u64 v[164:165], v[164:165], 0, s[12:13]
	global_store_dwordx4 v[164:165], v[92:95], off
	s_waitcnt vmcnt(14)
	v_lshlrev_b32_e32 v144, 16, v202
	v_and_b32_e32 v145, 0xffff0000, v202
	v_lshlrev_b32_e32 v146, 16, v203
	v_and_b32_e32 v147, 0xffff0000, v203
	v_lshlrev_b32_e32 v148, 16, v204
	v_and_b32_e32 v149, 0xffff0000, v204
	v_lshlrev_b32_e32 v150, 16, v205
	v_and_b32_e32 v151, 0xffff0000, v205
	global_load_dwordx4 v[202:205], v[168:169], off offset:256
	v_pk_fma_f32 v[84:85], v[84:85], v[44:45], v[144:145]
	v_pk_fma_f32 v[86:87], v[86:87], v[46:47], v[146:147]
	v_pk_fma_f32 v[80:81], v[80:81], v[40:41], v[148:149]
	v_pk_fma_f32 v[82:83], v[82:83], v[42:43], v[150:151]
	v_cvt_pk_bf16_f32 v84, v84, v85
	v_cvt_pk_bf16_f32 v85, v86, v87
	v_cvt_pk_bf16_f32 v86, v80, v81
	v_cvt_pk_bf16_f32 v87, v82, v83
	global_store_dwordx4 v[164:165], v[84:87], off offset:256
	s_waitcnt vmcnt(15)
	v_lshlrev_b32_e32 v144, 16, v174
	v_and_b32_e32 v145, 0xffff0000, v174
	v_lshlrev_b32_e32 v146, 16, v175
	v_and_b32_e32 v147, 0xffff0000, v175
	v_lshlrev_b32_e32 v148, 16, v176
	v_and_b32_e32 v149, 0xffff0000, v176
	v_lshlrev_b32_e32 v150, 16, v177
	v_and_b32_e32 v151, 0xffff0000, v177
	v_pk_fma_f32 v[76:77], v[76:77], v[60:61], v[144:145]
	v_pk_fma_f32 v[78:79], v[78:79], v[62:63], v[146:147]
	v_pk_fma_f32 v[72:73], v[72:73], v[56:57], v[148:149]
	v_pk_fma_f32 v[74:75], v[74:75], v[58:59], v[150:151]
	v_cvt_pk_bf16_f32 v76, v76, v77
	v_cvt_pk_bf16_f32 v77, v78, v79
	v_cvt_pk_bf16_f32 v78, v72, v73
	v_cvt_pk_bf16_f32 v79, v74, v75
	v_lshl_add_u64 v[164:165], v[164:165], 0, s[14:15]
	global_store_dwordx4 v[164:165], v[76:79], off
	s_waitcnt vmcnt(14)
	v_lshlrev_b32_e32 v144, 16, v178
	v_and_b32_e32 v145, 0xffff0000, v178
	v_lshlrev_b32_e32 v146, 16, v179
	v_and_b32_e32 v147, 0xffff0000, v179
	v_lshlrev_b32_e32 v148, 16, v180
	v_and_b32_e32 v149, 0xffff0000, v180
	v_lshlrev_b32_e32 v150, 16, v181
	v_and_b32_e32 v151, 0xffff0000, v181
	v_pk_fma_f32 v[68:69], v[68:69], v[44:45], v[144:145]
	v_pk_fma_f32 v[70:71], v[70:71], v[46:47], v[146:147]
	v_pk_fma_f32 v[64:65], v[64:65], v[40:41], v[148:149]
	v_pk_fma_f32 v[66:67], v[66:67], v[42:43], v[150:151]
	v_cvt_pk_bf16_f32 v68, v68, v69
	v_cvt_pk_bf16_f32 v69, v70, v71
	v_cvt_pk_bf16_f32 v70, v64, v65
	v_cvt_pk_bf16_f32 v71, v66, v67
	global_store_dwordx4 v[164:165], v[68:71], off offset:256
	s_waitcnt vmcnt(13)
; __device__ __forceinline__ unsigned cvt_pk_bf16(float lo, float hi) { unsigned r; asm volatile("v_cvt_pk_bf16_f32 %0, %1, %2" : "=v"(r) : "v"(lo), "v"(hi)); return r; }
;     __device__ __forceinline__ void operator()(const f32x4 (&acc)[2][2][4][2], const Unit& u, int wr, int wc, int fr, int fq) const {
;     ...
;                 for (int bj = 0; bj < 2; ++bj) {
;                     f32x4 b0, b1;
;                     if (!lat) { b0 = *(const f32x4*)(baseC + off + bj * HALF); b1 = *(const f32x4*)(baseC + off + bj * HALF + 4); }
;                     else if (baseLf) { b0 = *(const f32x4*)(baseLf + off + bj * HALF); b1 = *(const f32x4*)(baseLf + off + bj * HALF + 4); }
;                     else { const u32x4 w = *(const u32x4*)(baseLb + off + bj * HALF);
;                         b0 = (f32x4){__builtin_bit_cast(float, w.x << 16), __builtin_bit_cast(float, w.x & 0xffff0000u), __builtin_bit_cast(float, w.y << 16), __builtin_bit_cast(float, w.y & 0xffff0000u)};
;                         b1 = (f32x4){__builtin_bit_cast(float, w.z << 16), __builtin_bit_cast(float, w.z & 0xffff0000u), __builtin_bit_cast(float, w.w << 16), __builtin_bit_cast(float, w.w & 0xffff0000u)}; }
;                     const f32x4 o0 = b0 + g[bj][0] * acc[ai][bj][m][0], o1 = b1 + g[bj][1] * acc[ai][bj][m][1];
;                     if (!lat) { *(f32x4*)(outC + off + bj * HALF) = o0; *(f32x4*)(outC + off + bj * HALF + 4) = o1; }
;                     else { u32x4 w; w.x = cvt_pk_bf16(o0.x, o0.y); w.y = cvt_pk_bf16(o0.z, o0.w); w.z = cvt_pk_bf16(o1.x, o1.y); w.w = cvt_pk_bf16(o1.z, o1.w); *(u32x4*)(outL + off + bj * HALF) = w; }
	v_lshlrev_b32_e32 v144, 16, v182
	v_and_b32_e32 v145, 0xffff0000, v182
	v_lshlrev_b32_e32 v146, 16, v183
	v_and_b32_e32 v147, 0xffff0000, v183
	v_lshlrev_b32_e32 v148, 16, v184
	v_and_b32_e32 v149, 0xffff0000, v184
	v_lshlrev_b32_e32 v150, 16, v185
	v_and_b32_e32 v151, 0xffff0000, v185
	v_pk_fma_f32 v[52:53], v[52:53], v[60:61], v[144:145]
	v_pk_fma_f32 v[54:55], v[54:55], v[62:63], v[146:147]
	v_pk_fma_f32 v[48:49], v[48:49], v[56:57], v[148:149]
	v_pk_fma_f32 v[50:51], v[50:51], v[58:59], v[150:151]
	v_cvt_pk_bf16_f32 v52, v52, v53
	v_cvt_pk_bf16_f32 v53, v54, v55
	v_cvt_pk_bf16_f32 v54, v48, v49
	v_cvt_pk_bf16_f32 v55, v50, v51
	v_lshl_add_u64 v[164:165], v[164:165], 0, s[12:13]
	global_store_dwordx4 v[164:165], v[52:55], off
	s_waitcnt vmcnt(12)
	v_lshlrev_b32_e32 v144, 16, v186
	v_and_b32_e32 v145, 0xffff0000, v186
	v_lshlrev_b32_e32 v146, 16, v187
	v_and_b32_e32 v147, 0xffff0000, v187
	v_lshlrev_b32_e32 v148, 16, v188
	v_and_b32_e32 v149, 0xffff0000, v188
	v_lshlrev_b32_e32 v150, 16, v189
	v_and_b32_e32 v151, 0xffff0000, v189
	v_pk_fma_f32 v[36:37], v[36:37], v[44:45], v[144:145]
	v_pk_fma_f32 v[38:39], v[38:39], v[46:47], v[146:147]
	v_pk_fma_f32 v[32:33], v[32:33], v[40:41], v[148:149]
	v_pk_fma_f32 v[34:35], v[34:35], v[42:43], v[150:151]
	v_cvt_pk_bf16_f32 v36, v36, v37
	v_cvt_pk_bf16_f32 v37, v38, v39
	v_cvt_pk_bf16_f32 v38, v32, v33
	v_cvt_pk_bf16_f32 v39, v34, v35
	global_store_dwordx4 v[164:165], v[36:39], off offset:256
	s_waitcnt vmcnt(11)
	v_lshlrev_b32_e32 v144, 16, v190
	v_and_b32_e32 v145, 0xffff0000, v190
	v_lshlrev_b32_e32 v146, 16, v191
	v_and_b32_e32 v147, 0xffff0000, v191
	v_lshlrev_b32_e32 v148, 16, v192
	v_and_b32_e32 v149, 0xffff0000, v192
	v_lshlrev_b32_e32 v150, 16, v193
	v_and_b32_e32 v151, 0xffff0000, v193
	v_pk_fma_f32 v[28:29], v[28:29], v[60:61], v[144:145]
	v_pk_fma_f32 v[30:31], v[30:31], v[62:63], v[146:147]
	v_pk_fma_f32 v[24:25], v[24:25], v[56:57], v[148:149]
	v_pk_fma_f32 v[26:27], v[26:27], v[58:59], v[150:151]
	v_cvt_pk_bf16_f32 v28, v28, v29
	v_cvt_pk_bf16_f32 v29, v30, v31
	v_cvt_pk_bf16_f32 v30, v24, v25
	v_cvt_pk_bf16_f32 v31, v26, v27
	v_lshl_add_u64 v[164:165], v[164:165], 0, s[12:13]
	global_store_dwordx4 v[164:165], v[28:31], off
	s_waitcnt vmcnt(10)
	v_lshlrev_b32_e32 v144, 16, v194
	v_and_b32_e32 v145, 0xffff0000, v194
	v_lshlrev_b32_e32 v146, 16, v195
	v_and_b32_e32 v147, 0xffff0000, v195
	v_lshlrev_b32_e32 v148, 16, v196
	v_and_b32_e32 v149, 0xffff0000, v196
	v_lshlrev_b32_e32 v150, 16, v197
	v_and_b32_e32 v151, 0xffff0000, v197
	v_pk_fma_f32 v[20:21], v[20:21], v[44:45], v[144:145]
	v_pk_fma_f32 v[22:23], v[22:23], v[46:47], v[146:147]
	v_pk_fma_f32 v[16:17], v[16:17], v[40:41], v[148:149]
	v_pk_fma_f32 v[18:19], v[18:19], v[42:43], v[150:151]
	v_cvt_pk_bf16_f32 v20, v20, v21
	v_cvt_pk_bf16_f32 v21, v22, v23
	v_cvt_pk_bf16_f32 v22, v16, v17
	v_cvt_pk_bf16_f32 v23, v18, v19
	global_store_dwordx4 v[164:165], v[20:23], off offset:256
	s_waitcnt vmcnt(9)
	v_lshlrev_b32_e32 v144, 16, v198
	v_and_b32_e32 v145, 0xffff0000, v198
	v_lshlrev_b32_e32 v146, 16, v199
	v_and_b32_e32 v147, 0xffff0000, v199
	v_lshlrev_b32_e32 v148, 16, v200
	v_and_b32_e32 v149, 0xffff0000, v200
	v_lshlrev_b32_e32 v150, 16, v201
	v_and_b32_e32 v151, 0xffff0000, v201
	v_pk_fma_f32 v[12:13], v[12:13], v[60:61], v[144:145]
	v_pk_fma_f32 v[14:15], v[14:15], v[62:63], v[146:147]
	v_pk_fma_f32 v[8:9], v[8:9], v[56:57], v[148:149]
	v_pk_fma_f32 v[10:11], v[10:11], v[58:59], v[150:151]
	v_cvt_pk_bf16_f32 v12, v12, v13
	v_cvt_pk_bf16_f32 v13, v14, v15
	v_cvt_pk_bf16_f32 v14, v8, v9
	v_cvt_pk_bf16_f32 v15, v10, v11
	v_lshl_add_u64 v[164:165], v[164:165], 0, s[12:13]
	global_store_dwordx4 v[164:165], v[12:15], off
	s_waitcnt vmcnt(8)
	v_lshlrev_b32_e32 v144, 16, v202
	v_and_b32_e32 v145, 0xffff0000, v202
	v_lshlrev_b32_e32 v146, 16, v203
	v_and_b32_e32 v147, 0xffff0000, v203
	v_lshlrev_b32_e32 v148, 16, v204
	v_and_b32_e32 v149, 0xffff0000, v204
	v_lshlrev_b32_e32 v150, 16, v205
	v_and_b32_e32 v151, 0xffff0000, v205
	v_pk_fma_f32 v[4:5], v[4:5], v[44:45], v[144:145]
	v_pk_fma_f32 v[6:7], v[6:7], v[46:47], v[146:147]
	v_pk_fma_f32 v[0:1], v[0:1], v[40:41], v[148:149]
	v_pk_fma_f32 v[2:3], v[2:3], v[42:43], v[150:151]
	v_cvt_pk_bf16_f32 v4, v4, v5
	v_cvt_pk_bf16_f32 v5, v6, v7
	v_cvt_pk_bf16_f32 v6, v0, v1
	v_cvt_pk_bf16_f32 v7, v2, v3
	global_store_dwordx4 v[164:165], v[4:7], off offset:256
	s_mov_b64 s[40:41], -1
	s_mov_b64 s[48:49], -1
	s_branch .Lep2_join

; __device__ __forceinline__ unsigned cvt_pk_bf16(float lo, float hi) { unsigned r; asm volatile("v_cvt_pk_bf16_f32 %0, %1, %2" : "=v"(r) : "v"(lo), "v"(hi)); return r; }
;     __device__ __forceinline__ void operator()(const f32x4 (&acc)[2][2][4][2], const Unit& u, int wr, int wc, int fr, int fq) const {
;         const bool lat = u.pm < NLAT / BM; const int bb = lat ? (u.pm >> 5) : 4;
;         const int row0 = (lat ? u.pm * BM : u.pm * BM - NLAT) + wr * 64 + fr, col0 = u.pn * BM + wc * 32 + 8 * fq;
;         f32x4 g[2][2];
; #pragma unroll
;         for (int bj = 0; bj < 2; ++bj)
; #pragma unroll
;             for (int n = 0; n < 2; ++n) g[bj][n] = *(const f32x4*)(gate + bb * 6144 + col0 + bj * HALF + n * 4);
; #pragma unroll
;         for (int ai = 0; ai < 2; ++ai)
; #pragma unroll
;             for (int m = 0; m < 4; ++m) {
;                 const size_t off = (size_t)(row0 + ai * HALF + m * 16) * 1024 + col0;
; #pragma unroll
;                 for (int bj = 0; bj < 2; ++bj) {
;                     f32x4 b0, b1;
;                     if (!lat) { b0 = *(const f32x4*)(baseC + off + bj * HALF); b1 = *(const f32x4*)(baseC + off + bj * HALF + 4); }
;                     else if (baseLf) { b0 = *(const f32x4*)(baseLf + off + bj * HALF); b1 = *(const f32x4*)(baseLf + off + bj * HALF + 4); }
;                     else { const u32x4 w = *(const u32x4*)(baseLb + off + bj * HALF);
;                         b0 = (f32x4){__builtin_bit_cast(float, w.x << 16), __builtin_bit_cast(float, w.x & 0xffff0000u), __builtin_bit_cast(float, w.y << 16), __builtin_bit_cast(float, w.y & 0xffff0000u)};
;                         b1 = (f32x4){__builtin_bit_cast(float, w.z << 16), __builtin_bit_cast(float, w.z & 0xffff0000u), __builtin_bit_cast(float, w.w << 16), __builtin_bit_cast(float, w.w & 0xffff0000u)}; }
;                     const f32x4 o0 = b0 + g[bj][0] * acc[ai][bj][m][0], o1 = b1 + g[bj][1] * acc[ai][bj][m][1];
;                     if (!lat) { *(f32x4*)(outC + off + bj * HALF) = o0; *(f32x4*)(outC + off + bj * HALF + 4) = o1; }
;                     else { u32x4 w; w.x = cvt_pk_bf16(o0.x, o0.y); w.y = cvt_pk_bf16(o0.z, o0.w); w.z = cvt_pk_bf16(o1.x, o1.y); w.w = cvt_pk_bf16(o1.z, o1.w); *(u32x4*)(outL + off + bj * HALF) = w; }
.LBB0_993:
	s_cmpk_gt_i32 s63, 0x7f
	s_cselect_b64 s[48:49], -1, 0
	s_lshl_b32 s15, s63, 8
	s_lshr_b32 s14, s63, 5
	s_add_i32 s16, s15, 0xffff8000
	s_cmpk_lt_i32 s63, 0x80
	s_cselect_b64 s[12:13], -1, 0
	s_mulk_i32 s14, 0x1800
	s_and_b64 vcc, s[12:13], exec
	s_cselect_b32 s12, s14, 0x6000
	s_cselect_b32 s14, s15, s16
	s_ashr_i32 s13, s12, 31
	s_lshl_b64 s[12:13], s[12:13], 2
	v_lshl_or_b32 v162, s62, 8, v172
	s_add_u32 s12, s42, s12
	s_addc_u32 s13, s43, s13
	v_ashrrev_i32_e32 v163, 31, v162
	v_lshl_add_u64 v[60:61], v[162:163], 2, s[12:13]
	global_load_dwordx4 v[72:75], v[60:61], off offset:16
	global_load_dwordx4 v[76:79], v[60:61], off
	global_load_dwordx4 v[56:59], v[60:61], off offset:528
	s_nop 0
	global_load_dwordx4 v[60:63], v[60:61], off offset:512
	v_add_u32_e32 v164, s14, v170
	v_ashrrev_i32_e32 v165, 31, v164
	v_lshlrev_b64 v[144:145], 10, v[164:165]
	v_lshl_add_u64 v[168:169], v[144:145], 0, v[162:163]
	s_mov_b64 s[40:41], -1
	v_lshl_add_u64 v[166:167], v[168:169], 2, s[26:27]
	s_cbranch_vccz .Lep4_slow
	v_lshl_add_u64 v[168:169], v[168:169], 1, s[6:7]
	s_mov_b64 s[12:13], 0x8000
	s_mov_b64 s[14:15], 0x28000
	v_mov_b32_e32 v164, v168
	v_mov_b32_e32 v165, v169
	global_load_dwordx4 v[174:177], v[168:169], off
	global_load_dwordx4 v[178:181], v[168:169], off offset:256
	v_lshl_add_u64 v[168:169], v[168:169], 0, s[12:13]
	global_load_dwordx4 v[182:185], v[168:169], off
	global_load_dwordx4 v[186:189], v[168:169], off offset:256
	v_lshl_add_u64 v[168:169], v[168:169], 0, s[12:13]
	global_load_dwordx4 v[190:193], v[168:169], off
	global_load_dwordx4 v[194:197], v[168:169], off offset:256
	v_lshl_add_u64 v[168:169], v[168:169], 0, s[12:13]
	global_load_dwordx4 v[198:201], v[168:169], off
	global_load_dwordx4 v[202:205], v[168:169], off offset:256
	s_waitcnt vmcnt(7)
	v_lshlrev_b32_e32 v144, 16, v174
	v_and_b32_e32 v145, 0xffff0000, v174
	v_lshlrev_b32_e32 v146, 16, v175
	v_and_b32_e32 v147, 0xffff0000, v175
	v_lshlrev_b32_e32 v148, 16, v176
	v_and_b32_e32 v149, 0xffff0000, v176
	v_lshlrev_b32_e32 v150, 16, v177
	v_and_b32_e32 v151, 0xffff0000, v177
	v_lshl_add_u64 v[168:169], v[168:169], 0, s[14:15]
	global_load_dwordx4 v[174:177], v[168:169], off
	v_pk_fma_f32 v[140:141], v[140:141], v[76:77], v[144:145]
	v_pk_fma_f32 v[142:143], v[142:143], v[78:79], v[146:147]
	v_pk_fma_f32 v[136:137], v[136:137], v[72:73], v[148:149]
	v_pk_fma_f32 v[138:139], v[138:139], v[74:75], v[150:151]
	v_cvt_pk_bf16_f32 v140, v140, v141
	v_cvt_pk_bf16_f32 v141, v142, v143
	v_cvt_pk_bf16_f32 v142, v136, v137
	v_cvt_pk_bf16_f32 v143, v138, v139
	global_store_dwordx4 v[164:165], v[140:143], off
	s_waitcnt vmcnt(8)
	v_lshlrev_b32_e32 v144, 16, v178
	v_and_b32_e32 v145, 0xffff0000, v178
	v_lshlrev_b32_e32 v146, 16, v179
	v_and_b32_e32 v147, 0xffff0000, v179
	v_lshlrev_b32_e32 v148, 16, v180
	v_and_b32_e32 v149, 0xffff0000, v180
	v_lshlrev_b32_e32 v150, 16, v181
	v_and_b32_e32 v151, 0xffff0000, v181
	global_load_dwordx4 v[178:181], v[168:169], off offset:256
	v_pk_fma_f32 v[132:133], v[132:133], v[60:61], v[144:145]
	v_pk_fma_f32 v[134:135], v[134:135], v[62:63], v[146:147]
	v_pk_fma_f32 v[128:129], v[128:129], v[56:57], v[148:149]
	v_pk_fma_f32 v[130:131], v[130:131], v[58:59], v[150:151]
	v_cvt_pk_bf16_f32 v132, v132, v133
	v_cvt_pk_bf16_f32 v133, v134, v135
	v_cvt_pk_bf16_f32 v134, v128, v129
	v_cvt_pk_bf16_f32 v135, v130, v131
	global_store_dwordx4 v[164:165], v[132:135], off offset:256
	s_waitcnt vmcnt(9)
	v_lshlrev_b32_e32 v144, 16, v182
	v_and_b32_e32 v145, 0xffff0000, v182
	v_lshlrev_b32_e32 v146, 16, v183
	v_and_b32_e32 v147, 0xffff0000, v183
	v_lshlrev_b32_e32 v148, 16, v184
	v_and_b32_e32 v149, 0xffff0000, v184
	v_lshlrev_b32_e32 v150, 16, v185
	v_and_b32_e32 v151, 0xffff0000, v185
	v_lshl_add_u64 v[168:169], v[168:169], 0, s[12:13]
	global_load_dwordx4 v[182:185], v[168:169], off
	v_pk_fma_f32 v[124:125], v[124:125], v[76:77], v[144:145]
	v_pk_fma_f32 v[126:127], v[126:127], v[78:79], v[146:147]
	v_pk_fma_f32 v[120:121], v[120:121], v[72:73], v[148:149]
	v_pk_fma_f32 v[122:123], v[122:123], v[74:75], v[150:151]
	v_cvt_pk_bf16_f32 v124, v124, v125
	v_cvt_pk_bf16_f32 v125, v126, v127
	v_cvt_pk_bf16_f32 v126, v120, v121
	v_cvt_pk_bf16_f32 v127, v122, v123
	v_lshl_add_u64 v[164:165], v[164:165], 0, s[12:13]
	global_store_dwordx4 v[164:165], v[124:127], off
	s_waitcnt vmcnt(10)
	v_lshlrev_b32_e32 v144, 16, v186
	v_and_b32_e32 v145, 0xffff0000, v186
	v_lshlrev_b32_e32 v146, 16, v187
	v_and_b32_e32 v147, 0xffff0000, v187
	v_lshlrev_b32_e32 v148, 16, v188
	v_and_b32_e32 v149, 0xffff0000, v188
	v_lshlrev_b32_e32 v150, 16, v189
	v_and_b32_e32 v151, 0xffff0000, v189
	global_load_dwordx4 v[186:189], v[168:169], off offset:256
	v_pk_fma_f32 v[116:117], v[116:117], v[60:61], v[144:145]
	v_pk_fma_f32 v[118:119], v[118:119], v[62:63], v[146:147]
	v_pk_fma_f32 v[112:113], v[112:113], v[56:57], v[148:149]
	v_pk_fma_f32 v[114:115], v[114:115], v[58:59], v[150:151]
	v_cvt_pk_bf16_f32 v116, v116, v117
	v_cvt_pk_bf16_f32 v117, v118, v119
	v_cvt_pk_bf16_f32 v118, v112, v113
	v_cvt_pk_bf16_f32 v119, v114, v115
	global_store_dwordx4 v[164:165], v[116:119], off offset:256
	s_waitcnt vmcnt(11)
	v_lshlrev_b32_e32 v144, 16, v190
	v_and_b32_e32 v145, 0xffff0000, v190
	v_lshlrev_b32_e32 v146, 16, v191
	v_and_b32_e32 v147, 0xffff0000, v191
	v_lshlrev_b32_e32 v148, 16, v192
	v_and_b32_e32 v149, 0xffff0000, v192
	v_lshlrev_b32_e32 v150, 16, v193
	v_and_b32_e32 v151, 0xffff0000, v193
	v_lshl_add_u64 v[168:169], v[168:169], 0, s[12:13]
	global_load_dwordx4 v[190:193], v[168:169], off
	v_pk_fma_f32 v[108:109], v[108:109], v[76:77], v[144:145]
	v_pk_fma_f32 v[110:111], v[110:111], v[78:79], v[146:147]
	v_pk_fma_f32 v[104:105], v[104:105], v[72:73], v[148:149]
	v_pk_fma_f32 v[106:107], v[106:107], v[74:75], v[150:151]
	v_cvt_pk_bf16_f32 v108, v108, v109
	v_cvt_pk_bf16_f32 v109, v110, v111
	v_cvt_pk_bf16_f32 v110, v104, v105
	v_cvt_pk_bf16_f32 v111, v106, v107
	v_lshl_add_u64 v[164:165], v[164:165], 0, s[12:13]
	global_store_dwordx4 v[164:165], v[108:111], off
	s_waitcnt vmcnt(12)
; __device__ __forceinline__ unsigned cvt_pk_bf16(float lo, float hi) { unsigned r; asm volatile("v_cvt_pk_bf16_f32 %0, %1, %2" : "=v"(r) : "v"(lo), "v"(hi)); return r; }
;     __device__ __forceinline__ void operator()(const f32x4 (&acc)[2][2][4][2], const Unit& u, int wr, int wc, int fr, int fq) const {
;     ...
;                 for (int bj = 0; bj < 2; ++bj) {
;                     f32x4 b0, b1;
;                     if (!lat) { b0 = *(const f32x4*)(baseC + off + bj * HALF); b1 = *(const f32x4*)(baseC + off + bj * HALF + 4); }
;                     else if (baseLf) { b0 = *(const f32x4*)(baseLf + off + bj * HALF); b1 = *(const f32x4*)(baseLf + off + bj * HALF + 4); }
;                     else { const u32x4 w = *(const u32x4*)(baseLb + off + bj * HALF);
;                         b0 = (f32x4){__builtin_bit_cast(float, w.x << 16), __builtin_bit_cast(float, w.x & 0xffff0000u), __builtin_bit_cast(float, w.y << 16), __builtin_bit_cast(float, w.y & 0xffff0000u)};
;                         b1 = (f32x4){__builtin_bit_cast(float, w.z << 16), __builtin_bit_cast(float, w.z & 0xffff0000u), __builtin_bit_cast(float, w.w << 16), __builtin_bit_cast(float, w.w & 0xffff0000u)}; }
;                     const f32x4 o0 = b0 + g[bj][0] * acc[ai][bj][m][0], o1 = b1 + g[bj][1] * acc[ai][bj][m][1];
;                     if (!lat) { *(f32x4*)(outC + off + bj * HALF) = o0; *(f32x4*)(outC + off + bj * HALF + 4) = o1; }
;                     else { u32x4 w; w.x = cvt_pk_bf16(o0.x, o0.y); w.y = cvt_pk_bf16(o0.z, o0.w); w.z = cvt_pk_bf16(o1.x, o1.y); w.w = cvt_pk_bf16(o1.z, o1.w); *(u32x4*)(outL + off + bj * HALF) = w; }
	v_lshlrev_b32_e32 v144, 16, v194
	v_and_b32_e32 v145, 0xffff0000, v194
	v_lshlrev_b32_e32 v146, 16, v195
	v_and_b32_e32 v147, 0xffff0000, v195
	v_lshlrev_b32_e32 v148, 16, v196
	v_and_b32_e32 v149, 0xffff0000, v196
	v_lshlrev_b32_e32 v150, 16, v197
	v_and_b32_e32 v151, 0xffff0000, v197
	global_load_dwordx4 v[194:197], v[168:169], off offset:256
	v_pk_fma_f32 v[100:101], v[100:101], v[60:61], v[144:145]
	v_pk_fma_f32 v[102:103], v[102:103], v[62:63], v[146:147]
	v_pk_fma_f32 v[96:97], v[96:97], v[56:57], v[148:149]
	v_pk_fma_f32 v[98:99], v[98:99], v[58:59], v[150:151]
	v_cvt_pk_bf16_f32 v100, v100, v101
	v_cvt_pk_bf16_f32 v101, v102, v103
	v_cvt_pk_bf16_f32 v102, v96, v97
	v_cvt_pk_bf16_f32 v103, v98, v99
	global_store_dwordx4 v[164:165], v[100:103], off offset:256
	s_waitcnt vmcnt(13)
	v_lshlrev_b32_e32 v144, 16, v198
	v_and_b32_e32 v145, 0xffff0000, v198
	v_lshlrev_b32_e32 v146, 16, v199
	v_and_b32_e32 v147, 0xffff0000, v199
	v_lshlrev_b32_e32 v148, 16, v200
	v_and_b32_e32 v149, 0xffff0000, v200
	v_lshlrev_b32_e32 v150, 16, v201
	v_and_b32_e32 v151, 0xffff0000, v201
	v_lshl_add_u64 v[168:169], v[168:169], 0, s[12:13]
	global_load_dwordx4 v[198:201], v[168:169], off
	v_pk_fma_f32 v[92:93], v[92:93], v[76:77], v[144:145]
	v_pk_fma_f32 v[94:95], v[94:95], v[78:79], v[146:147]
	v_pk_fma_f32 v[88:89], v[88:89], v[72:73], v[148:149]
	v_pk_fma_f32 v[90:91], v[90:91], v[74:75], v[150:151]
	v_cvt_pk_bf16_f32 v92, v92, v93
	v_cvt_pk_bf16_f32 v93, v94, v95
	v_cvt_pk_bf16_f32 v94, v88, v89
	v_cvt_pk_bf16_f32 v95, v90, v91
	v_lshl_add_u64 v[164:165], v[164:165], 0, s[12:13]
	global_store_dwordx4 v[164:165], v[92:95], off
	s_waitcnt vmcnt(14)
	v_lshlrev_b32_e32 v144, 16, v202
	v_and_b32_e32 v145, 0xffff0000, v202
	v_lshlrev_b32_e32 v146, 16, v203
	v_and_b32_e32 v147, 0xffff0000, v203
	v_lshlrev_b32_e32 v148, 16, v204
	v_and_b32_e32 v149, 0xffff0000, v204
	v_lshlrev_b32_e32 v150, 16, v205
	v_and_b32_e32 v151, 0xffff0000, v205
	global_load_dwordx4 v[202:205], v[168:169], off offset:256
	v_pk_fma_f32 v[84:85], v[84:85], v[60:61], v[144:145]
	v_pk_fma_f32 v[86:87], v[86:87], v[62:63], v[146:147]
	v_pk_fma_f32 v[80:81], v[80:81], v[56:57], v[148:149]
	v_pk_fma_f32 v[82:83], v[82:83], v[58:59], v[150:151]
	v_cvt_pk_bf16_f32 v84, v84, v85
	v_cvt_pk_bf16_f32 v85, v86, v87
	v_cvt_pk_bf16_f32 v86, v80, v81
	v_cvt_pk_bf16_f32 v87, v82, v83
	global_store_dwordx4 v[164:165], v[84:87], off offset:256
	s_waitcnt vmcnt(15)
	v_lshlrev_b32_e32 v144, 16, v174
	v_and_b32_e32 v145, 0xffff0000, v174
	v_lshlrev_b32_e32 v146, 16, v175
	v_and_b32_e32 v147, 0xffff0000, v175
	v_lshlrev_b32_e32 v148, 16, v176
	v_and_b32_e32 v149, 0xffff0000, v176
	v_lshlrev_b32_e32 v150, 16, v177
	v_and_b32_e32 v151, 0xffff0000, v177
	v_pk_fma_f32 v[68:69], v[68:69], v[76:77], v[144:145]
	v_pk_fma_f32 v[70:71], v[70:71], v[78:79], v[146:147]
	v_pk_fma_f32 v[64:65], v[64:65], v[72:73], v[148:149]
	v_pk_fma_f32 v[66:67], v[66:67], v[74:75], v[150:151]
	v_cvt_pk_bf16_f32 v68, v68, v69
	v_cvt_pk_bf16_f32 v69, v70, v71
	v_cvt_pk_bf16_f32 v70, v64, v65
	v_cvt_pk_bf16_f32 v71, v66, v67
	v_lshl_add_u64 v[164:165], v[164:165], 0, s[14:15]
	global_store_dwordx4 v[164:165], v[68:71], off
	s_waitcnt vmcnt(14)
	v_lshlrev_b32_e32 v144, 16, v178
	v_and_b32_e32 v145, 0xffff0000, v178
	v_lshlrev_b32_e32 v146, 16, v179
	v_and_b32_e32 v147, 0xffff0000, v179
	v_lshlrev_b32_e32 v148, 16, v180
	v_and_b32_e32 v149, 0xffff0000, v180
	v_lshlrev_b32_e32 v150, 16, v181
	v_and_b32_e32 v151, 0xffff0000, v181
	v_pk_fma_f32 v[52:53], v[52:53], v[60:61], v[144:145]
	v_pk_fma_f32 v[54:55], v[54:55], v[62:63], v[146:147]
	v_pk_fma_f32 v[48:49], v[48:49], v[56:57], v[148:149]
	v_pk_fma_f32 v[50:51], v[50:51], v[58:59], v[150:151]
	v_cvt_pk_bf16_f32 v52, v52, v53
	v_cvt_pk_bf16_f32 v53, v54, v55
	v_cvt_pk_bf16_f32 v54, v48, v49
	v_cvt_pk_bf16_f32 v55, v50, v51
	global_store_dwordx4 v[164:165], v[52:55], off offset:256
	s_waitcnt vmcnt(13)
; __device__ __forceinline__ unsigned cvt_pk_bf16(float lo, float hi) { unsigned r; asm volatile("v_cvt_pk_bf16_f32 %0, %1, %2" : "=v"(r) : "v"(lo), "v"(hi)); return r; }
;     __device__ __forceinline__ void operator()(const f32x4 (&acc)[2][2][4][2], const Unit& u, int wr, int wc, int fr, int fq) const {
;     ...
;                 for (int bj = 0; bj < 2; ++bj) {
;                     f32x4 b0, b1;
;                     if (!lat) { b0 = *(const f32x4*)(baseC + off + bj * HALF); b1 = *(const f32x4*)(baseC + off + bj * HALF + 4); }
;                     else if (baseLf) { b0 = *(const f32x4*)(baseLf + off + bj * HALF); b1 = *(const f32x4*)(baseLf + off + bj * HALF + 4); }
;                     else { const u32x4 w = *(const u32x4*)(baseLb + off + bj * HALF);
;                         b0 = (f32x4){__builtin_bit_cast(float, w.x << 16), __builtin_bit_cast(float, w.x & 0xffff0000u), __builtin_bit_cast(float, w.y << 16), __builtin_bit_cast(float, w.y & 0xffff0000u)};
;                         b1 = (f32x4){__builtin_bit_cast(float, w.z << 16), __builtin_bit_cast(float, w.z & 0xffff0000u), __builtin_bit_cast(float, w.w << 16), __builtin_bit_cast(float, w.w & 0xffff0000u)}; }
;                     const f32x4 o0 = b0 + g[bj][0] * acc[ai][bj][m][0], o1 = b1 + g[bj][1] * acc[ai][bj][m][1];
;                     if (!lat) { *(f32x4*)(outC + off + bj * HALF) = o0; *(f32x4*)(outC + off + bj * HALF + 4) = o1; }
;                     else { u32x4 w; w.x = cvt_pk_bf16(o0.x, o0.y); w.y = cvt_pk_bf16(o0.z, o0.w); w.z = cvt_pk_bf16(o1.x, o1.y); w.w = cvt_pk_bf16(o1.z, o1.w); *(u32x4*)(outL + off + bj * HALF) = w; }
	v_lshlrev_b32_e32 v144, 16, v182
	v_and_b32_e32 v145, 0xffff0000, v182
	v_lshlrev_b32_e32 v146, 16, v183
	v_and_b32_e32 v147, 0xffff0000, v183
	v_lshlrev_b32_e32 v148, 16, v184
	v_and_b32_e32 v149, 0xffff0000, v184
	v_lshlrev_b32_e32 v150, 16, v185
	v_and_b32_e32 v151, 0xffff0000, v185
	v_pk_fma_f32 v[44:45], v[44:45], v[76:77], v[144:145]
	v_pk_fma_f32 v[46:47], v[46:47], v[78:79], v[146:147]
	v_pk_fma_f32 v[40:41], v[40:41], v[72:73], v[148:149]
	v_pk_fma_f32 v[42:43], v[42:43], v[74:75], v[150:151]
	v_cvt_pk_bf16_f32 v44, v44, v45
	v_cvt_pk_bf16_f32 v45, v46, v47
	v_cvt_pk_bf16_f32 v46, v40, v41
	v_cvt_pk_bf16_f32 v47, v42, v43
	v_lshl_add_u64 v[164:165], v[164:165], 0, s[12:13]
	global_store_dwordx4 v[164:165], v[44:47], off
	s_waitcnt vmcnt(12)
	v_lshlrev_b32_e32 v144, 16, v186
	v_and_b32_e32 v145, 0xffff0000, v186
	v_lshlrev_b32_e32 v146, 16, v187
	v_and_b32_e32 v147, 0xffff0000, v187
	v_lshlrev_b32_e32 v148, 16, v188
	v_and_b32_e32 v149, 0xffff0000, v188
	v_lshlrev_b32_e32 v150, 16, v189
	v_and_b32_e32 v151, 0xffff0000, v189
	v_pk_fma_f32 v[36:37], v[36:37], v[60:61], v[144:145]
	v_pk_fma_f32 v[38:39], v[38:39], v[62:63], v[146:147]
	v_pk_fma_f32 v[32:33], v[32:33], v[56:57], v[148:149]
	v_pk_fma_f32 v[34:35], v[34:35], v[58:59], v[150:151]
	v_cvt_pk_bf16_f32 v36, v36, v37
	v_cvt_pk_bf16_f32 v37, v38, v39
	v_cvt_pk_bf16_f32 v38, v32, v33
	v_cvt_pk_bf16_f32 v39, v34, v35
	global_store_dwordx4 v[164:165], v[36:39], off offset:256
	s_waitcnt vmcnt(11)
	v_lshlrev_b32_e32 v144, 16, v190
	v_and_b32_e32 v145, 0xffff0000, v190
	v_lshlrev_b32_e32 v146, 16, v191
	v_and_b32_e32 v147, 0xffff0000, v191
	v_lshlrev_b32_e32 v148, 16, v192
	v_and_b32_e32 v149, 0xffff0000, v192
	v_lshlrev_b32_e32 v150, 16, v193
	v_and_b32_e32 v151, 0xffff0000, v193
	v_pk_fma_f32 v[28:29], v[28:29], v[76:77], v[144:145]
	v_pk_fma_f32 v[30:31], v[30:31], v[78:79], v[146:147]
	v_pk_fma_f32 v[24:25], v[24:25], v[72:73], v[148:149]
	v_pk_fma_f32 v[26:27], v[26:27], v[74:75], v[150:151]
	v_cvt_pk_bf16_f32 v28, v28, v29
	v_cvt_pk_bf16_f32 v29, v30, v31
	v_cvt_pk_bf16_f32 v30, v24, v25
	v_cvt_pk_bf16_f32 v31, v26, v27
	v_lshl_add_u64 v[164:165], v[164:165], 0, s[12:13]
	global_store_dwordx4 v[164:165], v[28:31], off
	s_waitcnt vmcnt(10)
	v_lshlrev_b32_e32 v144, 16, v194
	v_and_b32_e32 v145, 0xffff0000, v194
	v_lshlrev_b32_e32 v146, 16, v195
	v_and_b32_e32 v147, 0xffff0000, v195
	v_lshlrev_b32_e32 v148, 16, v196
	v_and_b32_e32 v149, 0xffff0000, v196
	v_lshlrev_b32_e32 v150, 16, v197
	v_and_b32_e32 v151, 0xffff0000, v197
	v_pk_fma_f32 v[20:21], v[20:21], v[60:61], v[144:145]
	v_pk_fma_f32 v[22:23], v[22:23], v[62:63], v[146:147]
	v_pk_fma_f32 v[16:17], v[16:17], v[56:57], v[148:149]
	v_pk_fma_f32 v[18:19], v[18:19], v[58:59], v[150:151]
	v_cvt_pk_bf16_f32 v20, v20, v21
	v_cvt_pk_bf16_f32 v21, v22, v23
	v_cvt_pk_bf16_f32 v22, v16, v17
	v_cvt_pk_bf16_f32 v23, v18, v19
	global_store_dwordx4 v[164:165], v[20:23], off offset:256
	s_waitcnt vmcnt(9)
	v_lshlrev_b32_e32 v144, 16, v198
	v_and_b32_e32 v145, 0xffff0000, v198
	v_lshlrev_b32_e32 v146, 16, v199
	v_and_b32_e32 v147, 0xffff0000, v199
	v_lshlrev_b32_e32 v148, 16, v200
	v_and_b32_e32 v149, 0xffff0000, v200
	v_lshlrev_b32_e32 v150, 16, v201
	v_and_b32_e32 v151, 0xffff0000, v201
	v_pk_fma_f32 v[12:13], v[12:13], v[76:77], v[144:145]
	v_pk_fma_f32 v[14:15], v[14:15], v[78:79], v[146:147]
	v_pk_fma_f32 v[8:9], v[8:9], v[72:73], v[148:149]
	v_pk_fma_f32 v[10:11], v[10:11], v[74:75], v[150:151]
	v_cvt_pk_bf16_f32 v12, v12, v13
	v_cvt_pk_bf16_f32 v13, v14, v15
	v_cvt_pk_bf16_f32 v14, v8, v9
	v_cvt_pk_bf16_f32 v15, v10, v11
	v_lshl_add_u64 v[164:165], v[164:165], 0, s[12:13]
	global_store_dwordx4 v[164:165], v[12:15], off
	s_waitcnt vmcnt(8)
	v_lshlrev_b32_e32 v144, 16, v202
	v_and_b32_e32 v145, 0xffff0000, v202
	v_lshlrev_b32_e32 v146, 16, v203
	v_and_b32_e32 v147, 0xffff0000, v203
	v_lshlrev_b32_e32 v148, 16, v204
	v_and_b32_e32 v149, 0xffff0000, v204
	v_lshlrev_b32_e32 v150, 16, v205
	v_and_b32_e32 v151, 0xffff0000, v205
	v_pk_fma_f32 v[4:5], v[4:5], v[60:61], v[144:145]
	v_pk_fma_f32 v[6:7], v[6:7], v[62:63], v[146:147]
	v_pk_fma_f32 v[0:1], v[0:1], v[56:57], v[148:149]
	v_pk_fma_f32 v[2:3], v[2:3], v[58:59], v[150:151]
	v_cvt_pk_bf16_f32 v4, v4, v5
	v_cvt_pk_bf16_f32 v5, v6, v7
	v_cvt_pk_bf16_f32 v6, v0, v1
	v_cvt_pk_bf16_f32 v7, v2, v3
	global_store_dwordx4 v[164:165], v[4:7], off offset:256
	s_mov_b64 s[40:41], -1
	s_mov_b64 s[48:49], -1
	s_branch .Lep4_join
